# P4 EpiUp epilogue: second-half row-scale loads hoisted before stores; non-rope waves skip table-guard vmcnt waits
# speedup vs baseline: 1.0030x; 1.0012x over previous
.LBB0_1053:
	s_lshl_b32 s0, s50, 8
	s_add_i32 s0, s78, s0
	s_and_b32 s0, s0, 0x7fffff80
	s_lshl_b32 s0, s0, 1
	s_add_u32 s58, s79, s0
	s_addc_u32 s59, s82, 0
	s_lshl_b32 s0, s50, 2
	s_or_b32 s0, s0, s74
	s_mulk_i32 s0, 0x60
	s_ashr_i32 s1, s0, 31
	s_lshl_b64 s[0:1], s[0:1], 1
	s_add_u32 s54, s10, s0
	s_addc_u32 s55, s11, s1
	s_and_b64 s[0:1], s[8:9], exec
	s_cselect_b32 s0, s87, 0x340000
	s_add_u32 s50, s38, s0
	s_addc_u32 s51, s39, 0
	v_lshl_add_u64 v[4:5], v[200:201], 4, s[50:51]
	global_load_dwordx4 v[164:167], v[4:5], off
	global_load_dwordx4 v[236:239], v[4:5], off offset:2048
	global_load_dwordx4 v[240:243], v[4:5], off offset:2304
	global_load_dwordx4 v[244:247], v[4:5], off offset:2560
	global_load_dwordx4 v[248:251], v[4:5], off offset:2816
	v_add_u32_e32 v206, 16, v200
	v_add_u32_e32 v204, 32, v200
	v_add_u32_e32 v202, 48, v200
	v_ashrrev_i32_e32 v207, 31, v206
	v_ashrrev_i32_e32 v205, 31, v204
	v_ashrrev_i32_e32 v203, 31, v202
	v_lshl_add_u64 v[4:5], v[206:207], 4, s[50:51]
	v_lshl_add_u64 v[122:123], v[204:205], 4, s[50:51]
	v_lshl_add_u64 v[124:125], v[202:203], 4, s[50:51]
	global_load_dwordx4 v[178:181], v[4:5], off
	global_load_dwordx4 v[142:145], v[122:123], off
	s_nop 0
	global_load_dwordx4 v[122:125], v[124:125], off
	v_cndmask_b32_e64 v3, v218, v219, s[8:9]
	v_lshlrev_b64 v[210:211], 1, v[162:163]
	v_lshl_add_u64 v[198:199], v[8:9], 3, s[22:23]
	s_mov_b64 s[8:9], -1
	s_and_b64 vcc, exec, s[52:53]
	s_waitcnt vmcnt(0)
	v_mov_b32_e32 v4, v165
	v_mov_b32_e32 v5, v166
	v_mov_b32_e32 v165, v167
	v_pk_add_f32 v[4:5], v[4:5], v[164:165]
	s_nop 0
	v_add_f32_e32 v4, v4, v5
	v_fmaak_f32 v4, v3, v4, 0x358637bd
	v_rsq_f32_e32 v220, v4
	v_lshl_add_u64 v[4:5], s[58:59], 0, v[210:211]
	v_pk_mul_f32 v[160:161], v[160:161], v[220:221] op_sel_hi:[1,0]
	v_pk_mul_f32 v[208:209], v[158:159], v[220:221] op_sel_hi:[1,0]
	v_pk_mul_f32 v[156:157], v[156:157], v[220:221] op_sel_hi:[1,0]
	v_pk_mul_f32 v[158:159], v[154:155], v[220:221] op_sel_hi:[1,0]
	v_pk_mul_f32 v[152:153], v[152:153], v[220:221] op_sel_hi:[1,0]
	v_pk_mul_f32 v[154:155], v[150:151], v[220:221] op_sel_hi:[1,0]
	v_pk_mul_f32 v[148:149], v[148:149], v[220:221] op_sel_hi:[1,0]
	v_pk_mul_f32 v[150:151], v[146:147], v[220:221] op_sel_hi:[1,0]
	s_cbranch_vccz .LBB0_1063
	s_and_b64 vcc, exec, s[56:57]
	s_cbranch_vccz .LBB0_1060
	v_lshlrev_b64 v[146:147], 11, v[200:201]
	v_lshl_add_u64 v[146:147], v[4:5], 0, v[146:147]
	s_and_b64 vcc, exec, s[26:27]
	s_cbranch_vccz .LBB0_1057
	v_cvt_pk_bf16_f32 v162, v208, v209
	v_cvt_pk_bf16_f32 v163, v160, v161
	v_cvt_pk_bf16_f32 v164, v158, v159
	v_cvt_pk_bf16_f32 v165, v156, v157
	global_store_dwordx4 v[146:147], v[162:165], off
	s_mov_b64 s[8:9], 0
	s_nop 0
	v_cvt_pk_bf16_f32 v162, v154, v155
	v_cvt_pk_bf16_f32 v163, v152, v153
	v_cvt_pk_bf16_f32 v164, v150, v151
	v_cvt_pk_bf16_f32 v165, v148, v149
	global_store_dwordx4 v[146:147], v[162:165], off offset:64

.LBB0_1063:
	s_andn2_b64 vcc, exec, s[8:9]
	v_lshl_add_u64 v[146:147], s[54:55], 0, v[210:211]
	s_cbranch_vccnz .LBB0_1065
	v_mul_f32_e32 v7, v209, v209
	s_cmp_eq_u64 s[6:7], 0
	s_cbranch_scc1 .Lew4_0
	s_waitcnt vmcnt(4)
.Lew4_0:
	v_mul_f32_e32 v162, v161, v161
	v_fmac_f32_e32 v7, v208, v208
	v_fmac_f32_e32 v162, v160, v160
	v_add_f32_e32 v7, v7, v162
	v_mul_f32_e32 v162, v159, v159
	v_mul_f32_e32 v163, v157, v157
	v_fmac_f32_e32 v162, v158, v158
	v_fmac_f32_e32 v163, v156, v156
	v_add_f32_e32 v162, v162, v163
	v_add_f32_e32 v7, v7, v162
	v_mul_f32_e32 v162, v155, v155
	v_mul_f32_e32 v163, v153, v153
	v_fmac_f32_e32 v162, v154, v154
	v_fmac_f32_e32 v163, v152, v152
	v_add_f32_e32 v162, v162, v163
	v_mul_f32_e32 v163, v151, v151
	v_mul_f32_e32 v164, v149, v149
	v_fmac_f32_e32 v163, v150, v150
	v_fmac_f32_e32 v164, v148, v148
	v_add_f32_e32 v163, v163, v164
	v_add_f32_e32 v162, v162, v163
	v_add_f32_e32 v7, v7, v162
	v_mov_b32_e32 v162, v7
	s_nop 1
	v_permlane16_swap_b32_e32 v7, v162
	v_add_f32_e32 v7, v7, v162
	v_mov_b32_e32 v162, v7
	s_nop 1
	v_permlane32_swap_b32_e32 v7, v162
	v_add_f32_e32 v7, v7, v162
	v_fmamk_f32 v7, v7, 0x3c800000, v217
	v_rsq_f32_e32 v7, v7
	v_pk_mul_f32 v[164:165], v[38:39], v[208:209]
	v_pk_mul_f32 v[160:161], v[40:41], v[160:161]
	v_pk_mul_f32 v[166:167], v[36:37], v[156:157]
	v_mul_f32_e32 v7, 0x3e16c740, v7
	v_pk_mul_f32 v[158:159], v[34:35], v[158:159]
	v_mul_f32_e32 v156, v164, v7
	v_mul_f32_e32 v157, v165, v7
	v_cvt_pk_bf16_f32 v156, v156, v157
	v_mul_f32_e32 v157, v160, v7
	v_mul_f32_e32 v158, v158, v7
	v_mul_f32_e32 v159, v159, v7
	v_mad_i64_i32 v[162:163], s[0:1], v200, s70, v[146:147]
	v_mul_f32_e32 v160, v161, v7
	v_cvt_pk_bf16_f32 v157, v157, v160
	v_cvt_pk_bf16_f32 v158, v158, v159
	v_mul_f32_e32 v159, v166, v7
	v_pk_mul_f32 v[154:155], v[30:31], v[154:155]
	v_mul_f32_e32 v160, v167, v7
	v_cvt_pk_bf16_f32 v159, v159, v160
	global_store_dwordx4 v[162:163], v[156:159], off
	v_pk_mul_f32 v[152:153], v[32:33], v[152:153]
	v_pk_mul_f32 v[150:151], v[26:27], v[150:151]
	v_pk_mul_f32 v[156:157], v[28:29], v[148:149]
	v_mul_f32_e32 v148, v154, v7
	v_mul_f32_e32 v149, v155, v7
	v_cvt_pk_bf16_f32 v148, v148, v149
	v_mul_f32_e32 v149, v152, v7
	v_mul_f32_e32 v150, v150, v7
	v_mul_f32_e32 v151, v151, v7
	v_mul_f32_e32 v152, v153, v7
	v_cvt_pk_bf16_f32 v149, v149, v152
	v_cvt_pk_bf16_f32 v150, v150, v151
	v_mul_f32_e32 v151, v156, v7
	v_mul_f32_e32 v7, v157, v7
	v_cvt_pk_bf16_f32 v151, v151, v7
	global_store_dwordx4 v[162:163], v[148:151], off offset:64
	v_mov_b64_e32 v[166:167], v[170:171]
	v_mov_b64_e32 v[162:163], v[174:175]
	v_mov_b64_e32 v[168:169], v[172:173]
	v_mov_b64_e32 v[164:165], v[176:177]

.LBB0_1072:
	s_cmp_eq_u64 s[6:7], 0
	s_cbranch_scc1 .Lew4_1
	s_waitcnt vmcnt(4)
.Lew4_1:
	v_mov_b64_e32 v[126:127], v[162:163]
	v_mov_b64_e32 v[130:131], v[166:167]
	s_andn2_b64 vcc, exec, s[52:53]
	v_mov_b64_e32 v[128:129], v[164:165]
	v_mov_b64_e32 v[132:133], v[168:169]
	s_cbranch_vccnz .LBB0_1074
	v_ashrrev_i32_e32 v7, 31, v204
	v_lshrrev_b32_e32 v7, 19, v7
	v_add_u32_e32 v7, v204, v7
	v_and_b32_e32 v7, 0xffffe000, v7
	v_sub_u32_e32 v126, v204, v7
	v_ashrrev_i32_e32 v127, 31, v126
	v_lshlrev_b64 v[126:127], 7, v[126:127]
	v_lshl_add_u64 v[126:127], v[198:199], 0, v[126:127]
	global_load_dwordx4 v[130:133], v[126:127], off offset:16
	s_nop 0
	global_load_dwordx4 v[126:129], v[126:127], off
	v_mul_f32_e32 v7, v155, v155
	v_mul_f32_e32 v156, v151, v151
	v_fmac_f32_e32 v7, v154, v154
	v_fmac_f32_e32 v156, v150, v150
	v_add_f32_e32 v7, v7, v156
	v_mul_f32_e32 v156, v153, v153
	v_mul_f32_e32 v157, v149, v149
	v_fmac_f32_e32 v156, v152, v152
	v_fmac_f32_e32 v157, v148, v148
	v_add_f32_e32 v156, v156, v157
	v_add_f32_e32 v7, v7, v156
	v_mov_b32_e32 v156, v7
	s_nop 1
	v_permlane16_swap_b32_e32 v7, v156
	v_add_f32_e32 v7, v7, v156
	v_mov_b32_e32 v156, v7
	s_nop 1
	v_permlane32_swap_b32_e32 v7, v156
	v_add_f32_e32 v7, v7, v156
	v_fmamk_f32 v7, v7, 0x3d000000, v217
	v_rsq_f32_e32 v156, v7
	v_mov_b32_e32 v158, v154
	v_mov_b32_e32 v159, v152
	v_mov_b32_e32 v160, v38
	v_pk_mul_f32 v[158:159], v[158:159], v[156:157] op_sel_hi:[1,0]
	v_mov_b32_e32 v161, v34
	v_pk_mul_f32 v[158:159], v[160:161], v[158:159]
	s_nop 0
	v_pk_mul_f32 v[170:171], v[162:163], v[158:159]
	v_pk_mul_f32 v[158:159], v[162:163], v[158:159] op_sel:[1,0] op_sel_hi:[0,1]
	v_add_f32_e32 v157, v158, v159
	v_mov_b32_e32 v158, v155
	v_mov_b32_e32 v159, v153
	v_sub_f32_e32 v7, v170, v171
	v_pk_mul_f32 v[158:159], v[158:159], v[156:157] op_sel_hi:[1,0]
	v_mov_b32_e32 v170, v39
	v_mov_b32_e32 v171, v35
	v_pk_mul_f32 v[158:159], v[170:171], v[158:159]
	v_mul_f32_e32 v176, 0x3e16c740, v157
	v_pk_mul_f32 v[172:173], v[164:165], v[158:159]
	v_pk_mul_f32 v[158:159], v[164:165], v[158:159] op_sel:[1,0] op_sel_hi:[0,1]
	v_sub_f32_e32 v157, v172, v173
	v_mul_f32_e32 v177, 0x3e16c740, v157
	v_add_f32_e32 v157, v158, v159
	v_mov_b32_e32 v158, v150
	v_mov_b32_e32 v159, v148
	v_pk_mul_f32 v[158:159], v[158:159], v[156:157] op_sel_hi:[1,0]
	v_mov_b32_e32 v172, v40
	v_mov_b32_e32 v173, v36
	v_pk_mul_f32 v[158:159], v[172:173], v[158:159]
	v_mul_f32_e32 v178, 0x3e16c740, v157
	v_pk_mul_f32 v[174:175], v[166:167], v[158:159]
	v_pk_mul_f32 v[158:159], v[166:167], v[158:159] op_sel:[1,0] op_sel_hi:[0,1]
	v_sub_f32_e32 v157, v174, v175
	v_mul_f32_e32 v179, 0x3e16c740, v157
	v_add_f32_e32 v157, v158, v159
	v_mov_b32_e32 v158, v151
	v_mov_b32_e32 v159, v149
	v_mul_f32_e32 v180, 0x3e16c740, v157
	v_pk_mul_f32 v[156:157], v[158:159], v[156:157] op_sel_hi:[1,0]
	v_mov_b32_e32 v158, v41
	v_mov_b32_e32 v159, v37
	v_pk_mul_f32 v[156:157], v[158:159], v[156:157]
	v_mul_f32_e32 v7, 0x3e16c740, v7
	v_pk_mul_f32 v[174:175], v[168:169], v[156:157]
	v_pk_mul_f32 v[156:157], v[168:169], v[156:157] op_sel:[1,0] op_sel_hi:[0,1]
	v_add_f32_e32 v156, v156, v157
	v_mul_f32_e32 v181, 0x3e16c740, v156
	v_mov_b64_e32 v[156:157], s[28:29]
	v_sub_f32_e32 v174, v174, v175
	v_mad_i64_i32 v[156:157], s[0:1], v206, s70, v[156:157]
	v_mul_f32_e32 v175, 0x3e16c740, v174
	v_cvt_pk_bf16_f32 v174, v7, v177
	v_lshl_add_u64 v[156:157], v[8:9], 1, v[156:157]
	v_cvt_pk_bf16_f32 v175, v179, v175
	global_store_dwordx2 v[156:157], v[174:175], off offset:128
	v_cvt_pk_bf16_f32 v174, v176, v178
	v_mul_f32_e32 v7, v141, v141
	v_mul_f32_e32 v176, v137, v137
	v_fmac_f32_e32 v7, v140, v140
	v_fmac_f32_e32 v176, v136, v136
	v_add_f32_e32 v7, v7, v176
	v_mul_f32_e32 v176, v139, v139
	v_mul_f32_e32 v177, v135, v135
	v_fmac_f32_e32 v176, v138, v138
	v_fmac_f32_e32 v177, v134, v134
	v_add_f32_e32 v176, v176, v177
	v_add_f32_e32 v7, v7, v176
	v_mov_b32_e32 v176, v7
	s_nop 1
	v_permlane16_swap_b32_e32 v7, v176
	v_add_f32_e32 v7, v7, v176
	v_mov_b32_e32 v176, v7
	s_nop 1
	v_permlane32_swap_b32_e32 v7, v176
	v_add_f32_e32 v7, v7, v176
	v_fmamk_f32 v7, v7, 0x3d000000, v217
	v_rsq_f32_e32 v176, v7
	v_cvt_pk_bf16_f32 v175, v180, v181
	global_store_dwordx2 v[156:157], v[174:175], off offset:160
	v_mov_b32_e32 v174, v140
	v_mov_b32_e32 v175, v138
	v_pk_mul_f32 v[174:175], v[174:175], v[176:177] op_sel_hi:[1,0]
	s_nop 0
	v_pk_mul_f32 v[160:161], v[160:161], v[174:175]
	s_nop 0
	v_pk_mul_f32 v[174:175], v[162:163], v[160:161]
	v_pk_mul_f32 v[160:161], v[162:163], v[160:161] op_sel:[1,0] op_sel_hi:[0,1]
	v_add_f32_e32 v160, v160, v161
	v_sub_f32_e32 v7, v174, v175
	v_mul_f32_e32 v174, 0x3e16c740, v160
	v_mov_b32_e32 v160, v141
	v_mov_b32_e32 v161, v139
	v_pk_mul_f32 v[160:161], v[160:161], v[176:177] op_sel_hi:[1,0]
	v_mul_f32_e32 v7, 0x3e16c740, v7
	v_pk_mul_f32 v[160:161], v[170:171], v[160:161]
	s_nop 0
	v_pk_mul_f32 v[170:171], v[164:165], v[160:161]
	v_pk_mul_f32 v[160:161], v[164:165], v[160:161] op_sel:[1,0] op_sel_hi:[0,1]
	v_add_f32_e32 v160, v160, v161
	v_mul_f32_e32 v177, 0x3e16c740, v160
	v_mov_b32_e32 v160, v136
	v_mov_b32_e32 v161, v134
	v_pk_mul_f32 v[160:161], v[160:161], v[176:177] op_sel_hi:[1,0]
	v_sub_f32_e32 v170, v170, v171
	v_pk_mul_f32 v[160:161], v[172:173], v[160:161]
	v_mul_f32_e32 v175, 0x3e16c740, v170
	v_pk_mul_f32 v[170:171], v[166:167], v[160:161]
	v_pk_mul_f32 v[160:161], v[166:167], v[160:161] op_sel:[1,0] op_sel_hi:[0,1]
	v_add_f32_e32 v160, v160, v161
	v_sub_f32_e32 v170, v170, v171
	v_mul_f32_e32 v171, 0x3e16c740, v160
	v_mov_b32_e32 v160, v137
	v_mov_b32_e32 v161, v135
	v_pk_mul_f32 v[160:161], v[160:161], v[176:177] op_sel_hi:[1,0]
	v_mul_f32_e32 v170, 0x3e16c740, v170
	v_pk_mul_f32 v[158:159], v[158:159], v[160:161]
	s_nop 0
	v_pk_mul_f32 v[160:161], v[168:169], v[158:159]
	v_pk_mul_f32 v[158:159], v[168:169], v[158:159] op_sel:[1,0] op_sel_hi:[0,1]
	v_sub_f32_e32 v160, v160, v161
	v_add_f32_e32 v158, v158, v159
	v_mul_f32_e32 v160, 0x3e16c740, v160
	v_mul_f32_e32 v161, 0x3e16c740, v158
	v_cvt_pk_bf16_f32 v158, v7, v175
	v_cvt_pk_bf16_f32 v159, v170, v160
	global_store_dwordx2 v[156:157], v[158:159], off offset:320
	v_cvt_pk_bf16_f32 v158, v174, v177
	v_cvt_pk_bf16_f32 v159, v171, v161
	global_store_dwordx2 v[156:157], v[158:159], off offset:352

.LBB0_1075:
	s_andn2_b64 vcc, exec, s[52:53]
	s_cbranch_vccnz .LBB0_1077
	v_mul_f32_e32 v7, v155, v155
	s_cmp_eq_u64 s[6:7], 0
	s_cbranch_scc1 .Lew4_2
	s_waitcnt vmcnt(4)
.Lew4_2:
	v_mul_f32_e32 v126, v151, v151
	v_fmac_f32_e32 v7, v154, v154
	v_fmac_f32_e32 v126, v150, v150
	v_add_f32_e32 v7, v7, v126
	v_mul_f32_e32 v126, v153, v153
	v_mul_f32_e32 v127, v149, v149
	v_fmac_f32_e32 v126, v152, v152
	v_fmac_f32_e32 v127, v148, v148
	v_add_f32_e32 v126, v126, v127
	v_add_f32_e32 v7, v7, v126
	v_mul_f32_e32 v126, v141, v141
	v_mul_f32_e32 v127, v137, v137
	v_fmac_f32_e32 v126, v140, v140
	v_fmac_f32_e32 v127, v136, v136
	v_add_f32_e32 v126, v126, v127
	v_mul_f32_e32 v127, v139, v139
	v_mul_f32_e32 v128, v135, v135
	v_fmac_f32_e32 v127, v138, v138
	v_fmac_f32_e32 v128, v134, v134
	v_add_f32_e32 v127, v127, v128
	v_add_f32_e32 v126, v126, v127
	v_add_f32_e32 v7, v7, v126
	v_mov_b32_e32 v126, v7
	s_nop 1
	v_permlane16_swap_b32_e32 v7, v126
	v_add_f32_e32 v7, v7, v126
	v_mov_b32_e32 v126, v7
	s_nop 1
	v_permlane32_swap_b32_e32 v7, v126
	v_add_f32_e32 v7, v7, v126
	v_fmamk_f32 v7, v7, 0x3c800000, v217
	v_rsq_f32_e32 v7, v7
	v_pk_mul_f32 v[126:127], v[38:39], v[154:155]
	v_pk_mul_f32 v[128:129], v[40:41], v[150:151]
	v_pk_mul_f32 v[132:133], v[36:37], v[148:149]
	v_mul_f32_e32 v7, 0x3e16c740, v7
	v_mul_f32_e32 v126, v126, v7
	v_mul_f32_e32 v127, v127, v7
	v_pk_mul_f32 v[148:149], v[34:35], v[152:153]
	v_cvt_pk_bf16_f32 v126, v126, v127
	v_mul_f32_e32 v127, v128, v7
	v_mul_f32_e32 v128, v129, v7
	v_cvt_pk_bf16_f32 v127, v127, v128
	v_mul_f32_e32 v128, v148, v7
	v_mul_f32_e32 v129, v149, v7
	v_mad_i64_i32 v[130:131], s[0:1], v206, s70, v[146:147]
	v_cvt_pk_bf16_f32 v128, v128, v129
	v_mul_f32_e32 v129, v132, v7
	v_mul_f32_e32 v132, v133, v7
	v_cvt_pk_bf16_f32 v129, v129, v132
	global_store_dwordx4 v[130:131], v[126:129], off
	v_pk_mul_f32 v[132:133], v[28:29], v[134:135]
	v_pk_mul_f32 v[134:135], v[26:27], v[138:139]
	v_pk_mul_f32 v[126:127], v[30:31], v[140:141]
	v_pk_mul_f32 v[128:129], v[32:33], v[136:137]
	v_mul_f32_e32 v126, v126, v7
	v_mul_f32_e32 v127, v127, v7
	v_cvt_pk_bf16_f32 v126, v126, v127
	v_mul_f32_e32 v127, v128, v7
	v_mul_f32_e32 v128, v129, v7
	v_cvt_pk_bf16_f32 v127, v127, v128
	v_mul_f32_e32 v128, v134, v7
	v_mul_f32_e32 v129, v135, v7
	v_cvt_pk_bf16_f32 v128, v128, v129
	v_mul_f32_e32 v129, v132, v7
	v_mul_f32_e32 v7, v133, v7
	v_cvt_pk_bf16_f32 v129, v129, v7
	global_store_dwordx4 v[130:131], v[126:129], off offset:64
	v_mov_b64_e32 v[130:131], v[166:167]
	v_mov_b64_e32 v[132:133], v[168:169]
	v_mov_b64_e32 v[126:127], v[162:163]
	v_mov_b64_e32 v[128:129], v[164:165]

.Lew4_3:
	v_mov_b64_e32 v[106:107], v[126:127]
	v_mov_b64_e32 v[110:111], v[130:131]
	s_andn2_b64 vcc, exec, s[52:53]
	v_mov_b64_e32 v[108:109], v[128:129]
	v_mov_b64_e32 v[112:113], v[132:133]
	s_cbranch_vccnz .LBB0_1086
	v_ashrrev_i32_e32 v7, 31, v202
	v_lshrrev_b32_e32 v7, 19, v7
	v_add_u32_e32 v7, v202, v7
	v_and_b32_e32 v7, 0xffffe000, v7
	v_sub_u32_e32 v106, v202, v7
	v_ashrrev_i32_e32 v107, 31, v106
	v_lshlrev_b64 v[106:107], 7, v[106:107]
	v_lshl_add_u64 v[106:107], v[198:199], 0, v[106:107]
	global_load_dwordx4 v[110:113], v[106:107], off offset:16
	s_nop 0
	global_load_dwordx4 v[106:109], v[106:107], off
	v_mul_f32_e32 v7, v141, v141
	v_mul_f32_e32 v142, v137, v137
	v_fmac_f32_e32 v7, v140, v140
	v_fmac_f32_e32 v142, v136, v136
	v_add_f32_e32 v7, v7, v142
	v_mul_f32_e32 v142, v139, v139
	v_mul_f32_e32 v143, v135, v135
	v_fmac_f32_e32 v142, v138, v138
	v_fmac_f32_e32 v143, v134, v134
	v_add_f32_e32 v142, v142, v143
	v_add_f32_e32 v7, v7, v142
	v_mov_b32_e32 v142, v7
	s_nop 1
	v_permlane16_swap_b32_e32 v7, v142
	v_add_f32_e32 v7, v7, v142
	v_mov_b32_e32 v142, v7
	s_nop 1
	v_permlane32_swap_b32_e32 v7, v142
	v_add_f32_e32 v7, v7, v142
	v_fmamk_f32 v7, v7, 0x3d000000, v217
	v_rsq_f32_e32 v142, v7
	v_mov_b32_e32 v144, v140
	v_mov_b32_e32 v145, v138
	v_mov_b32_e32 v148, v38
	v_pk_mul_f32 v[144:145], v[144:145], v[142:143] op_sel_hi:[1,0]
	v_mov_b32_e32 v149, v34
	v_pk_mul_f32 v[144:145], v[148:149], v[144:145]
	s_nop 0
	v_pk_mul_f32 v[150:151], v[126:127], v[144:145]
	v_pk_mul_f32 v[144:145], v[126:127], v[144:145] op_sel:[1,0] op_sel_hi:[0,1]
	v_add_f32_e32 v143, v144, v145
	v_mov_b32_e32 v144, v141
	v_mov_b32_e32 v145, v139
	v_sub_f32_e32 v7, v150, v151
	v_pk_mul_f32 v[144:145], v[144:145], v[142:143] op_sel_hi:[1,0]
	v_mov_b32_e32 v150, v39
	v_mov_b32_e32 v151, v35
	v_pk_mul_f32 v[144:145], v[150:151], v[144:145]
	v_mul_f32_e32 v156, 0x3e16c740, v143
	v_pk_mul_f32 v[152:153], v[128:129], v[144:145]
	v_pk_mul_f32 v[144:145], v[128:129], v[144:145] op_sel:[1,0] op_sel_hi:[0,1]
	v_sub_f32_e32 v143, v152, v153
	v_mul_f32_e32 v157, 0x3e16c740, v143
	v_add_f32_e32 v143, v144, v145
	v_mov_b32_e32 v144, v136
	v_mov_b32_e32 v145, v134
	v_pk_mul_f32 v[144:145], v[144:145], v[142:143] op_sel_hi:[1,0]
	v_mov_b32_e32 v152, v40
	v_mov_b32_e32 v153, v36
	v_pk_mul_f32 v[144:145], v[152:153], v[144:145]
	v_mul_f32_e32 v158, 0x3e16c740, v143
	v_pk_mul_f32 v[154:155], v[130:131], v[144:145]
	v_pk_mul_f32 v[144:145], v[130:131], v[144:145] op_sel:[1,0] op_sel_hi:[0,1]
	v_sub_f32_e32 v143, v154, v155
	v_mul_f32_e32 v159, 0x3e16c740, v143
	v_add_f32_e32 v143, v144, v145
	v_mov_b32_e32 v144, v137
	v_mov_b32_e32 v145, v135
	v_mul_f32_e32 v160, 0x3e16c740, v143
	v_pk_mul_f32 v[142:143], v[144:145], v[142:143] op_sel_hi:[1,0]
	v_mov_b32_e32 v144, v41
	v_mov_b32_e32 v145, v37
	v_pk_mul_f32 v[142:143], v[144:145], v[142:143]
	v_mul_f32_e32 v7, 0x3e16c740, v7
	v_pk_mul_f32 v[154:155], v[132:133], v[142:143]
	v_pk_mul_f32 v[142:143], v[132:133], v[142:143] op_sel:[1,0] op_sel_hi:[0,1]
	v_add_f32_e32 v142, v142, v143
	v_mul_f32_e32 v161, 0x3e16c740, v142
	v_mov_b64_e32 v[142:143], s[28:29]
	v_sub_f32_e32 v154, v154, v155
	v_mad_i64_i32 v[142:143], s[0:1], v204, s70, v[142:143]
	v_mul_f32_e32 v155, 0x3e16c740, v154
	v_cvt_pk_bf16_f32 v154, v7, v157
	v_lshl_add_u64 v[142:143], v[8:9], 1, v[142:143]
	v_cvt_pk_bf16_f32 v155, v159, v155
	global_store_dwordx2 v[142:143], v[154:155], off offset:128
	v_cvt_pk_bf16_f32 v154, v156, v158
	v_mul_f32_e32 v7, v121, v121
	v_mul_f32_e32 v156, v117, v117
	v_fmac_f32_e32 v7, v120, v120
	v_fmac_f32_e32 v156, v116, v116
	v_add_f32_e32 v7, v7, v156
	v_mul_f32_e32 v156, v119, v119
	v_mul_f32_e32 v157, v115, v115
	v_fmac_f32_e32 v156, v118, v118
	v_fmac_f32_e32 v157, v114, v114
	v_add_f32_e32 v156, v156, v157
	v_add_f32_e32 v7, v7, v156
	v_mov_b32_e32 v156, v7
	s_nop 1
	v_permlane16_swap_b32_e32 v7, v156
	v_add_f32_e32 v7, v7, v156
	v_mov_b32_e32 v156, v7
	s_nop 1
	v_permlane32_swap_b32_e32 v7, v156
	v_add_f32_e32 v7, v7, v156
	v_fmamk_f32 v7, v7, 0x3d000000, v217
	v_rsq_f32_e32 v156, v7
	v_cvt_pk_bf16_f32 v155, v160, v161
	global_store_dwordx2 v[142:143], v[154:155], off offset:160
	v_mov_b32_e32 v154, v120
	v_mov_b32_e32 v155, v118
	v_pk_mul_f32 v[154:155], v[154:155], v[156:157] op_sel_hi:[1,0]
	s_nop 0
	v_pk_mul_f32 v[148:149], v[148:149], v[154:155]
	s_nop 0
	v_pk_mul_f32 v[154:155], v[126:127], v[148:149]
	v_pk_mul_f32 v[148:149], v[126:127], v[148:149] op_sel:[1,0] op_sel_hi:[0,1]
	v_add_f32_e32 v148, v148, v149
	v_sub_f32_e32 v7, v154, v155
	v_mul_f32_e32 v154, 0x3e16c740, v148
	v_mov_b32_e32 v148, v121
	v_mov_b32_e32 v149, v119
	v_pk_mul_f32 v[148:149], v[148:149], v[156:157] op_sel_hi:[1,0]
	v_mul_f32_e32 v7, 0x3e16c740, v7
	v_pk_mul_f32 v[148:149], v[150:151], v[148:149]
	s_nop 0
	v_pk_mul_f32 v[150:151], v[128:129], v[148:149]
	v_pk_mul_f32 v[148:149], v[128:129], v[148:149] op_sel:[1,0] op_sel_hi:[0,1]
	v_add_f32_e32 v148, v148, v149
	v_mul_f32_e32 v157, 0x3e16c740, v148
	v_mov_b32_e32 v148, v116
	v_mov_b32_e32 v149, v114
	v_pk_mul_f32 v[148:149], v[148:149], v[156:157] op_sel_hi:[1,0]
	v_sub_f32_e32 v150, v150, v151
	v_pk_mul_f32 v[148:149], v[152:153], v[148:149]
	v_mul_f32_e32 v155, 0x3e16c740, v150
	v_pk_mul_f32 v[150:151], v[130:131], v[148:149]
	v_pk_mul_f32 v[148:149], v[130:131], v[148:149] op_sel:[1,0] op_sel_hi:[0,1]
	v_add_f32_e32 v148, v148, v149
	v_sub_f32_e32 v150, v150, v151
	v_mul_f32_e32 v151, 0x3e16c740, v148
	v_mov_b32_e32 v148, v117
	v_mov_b32_e32 v149, v115
	v_pk_mul_f32 v[148:149], v[148:149], v[156:157] op_sel_hi:[1,0]
	v_mul_f32_e32 v150, 0x3e16c740, v150
	v_pk_mul_f32 v[144:145], v[144:145], v[148:149]
	s_nop 0
	v_pk_mul_f32 v[148:149], v[132:133], v[144:145]
	v_pk_mul_f32 v[144:145], v[132:133], v[144:145] op_sel:[1,0] op_sel_hi:[0,1]
	v_sub_f32_e32 v148, v148, v149
	v_add_f32_e32 v144, v144, v145
	v_mul_f32_e32 v148, 0x3e16c740, v148
	v_mul_f32_e32 v149, 0x3e16c740, v144
	v_cvt_pk_bf16_f32 v144, v7, v155
	v_cvt_pk_bf16_f32 v145, v150, v148
	global_store_dwordx2 v[142:143], v[144:145], off offset:320
	v_cvt_pk_bf16_f32 v144, v154, v157
	v_cvt_pk_bf16_f32 v145, v151, v149
	global_store_dwordx2 v[142:143], v[144:145], off offset:352

.LBB0_1087:
	s_andn2_b64 vcc, exec, s[52:53]
	s_cbranch_vccnz .LBB0_1089
	v_mul_f32_e32 v7, v141, v141
	s_cmp_eq_u64 s[6:7], 0
	s_cbranch_scc1 .Lew4_4
	s_waitcnt vmcnt(4)
.Lew4_4:
	v_mul_f32_e32 v106, v137, v137
	v_fmac_f32_e32 v7, v140, v140
	v_fmac_f32_e32 v106, v136, v136
	v_add_f32_e32 v7, v7, v106
	v_mul_f32_e32 v106, v139, v139
	v_mul_f32_e32 v107, v135, v135
	v_fmac_f32_e32 v106, v138, v138
	v_fmac_f32_e32 v107, v134, v134
	v_add_f32_e32 v106, v106, v107
	v_add_f32_e32 v7, v7, v106
	v_mul_f32_e32 v106, v121, v121
	v_mul_f32_e32 v107, v117, v117
	v_fmac_f32_e32 v106, v120, v120
	v_fmac_f32_e32 v107, v116, v116
	v_add_f32_e32 v106, v106, v107
	v_mul_f32_e32 v107, v119, v119
	v_mul_f32_e32 v108, v115, v115
	v_fmac_f32_e32 v107, v118, v118
	v_fmac_f32_e32 v108, v114, v114
	v_add_f32_e32 v107, v107, v108
	v_add_f32_e32 v106, v106, v107
	v_add_f32_e32 v7, v7, v106
	v_mov_b32_e32 v106, v7
	s_nop 1
	v_permlane16_swap_b32_e32 v7, v106
	v_add_f32_e32 v7, v7, v106
	v_mov_b32_e32 v106, v7
	s_nop 1
	v_permlane32_swap_b32_e32 v7, v106
	v_add_f32_e32 v7, v7, v106
	v_fmamk_f32 v7, v7, 0x3c800000, v217
	v_rsq_f32_e32 v7, v7
	v_pk_mul_f32 v[106:107], v[38:39], v[140:141]
	v_pk_mul_f32 v[108:109], v[40:41], v[136:137]
	v_pk_mul_f32 v[112:113], v[36:37], v[134:135]
	v_mul_f32_e32 v7, 0x3e16c740, v7
	v_mul_f32_e32 v106, v106, v7
	v_mul_f32_e32 v107, v107, v7
	v_pk_mul_f32 v[134:135], v[34:35], v[138:139]
	v_cvt_pk_bf16_f32 v106, v106, v107
	v_mul_f32_e32 v107, v108, v7
	v_mul_f32_e32 v108, v109, v7
	v_cvt_pk_bf16_f32 v107, v107, v108
	v_mul_f32_e32 v108, v134, v7
	v_mul_f32_e32 v109, v135, v7
	v_mad_i64_i32 v[110:111], s[0:1], v204, s70, v[146:147]
	v_cvt_pk_bf16_f32 v108, v108, v109
	v_mul_f32_e32 v109, v112, v7
	v_mul_f32_e32 v112, v113, v7
	v_cvt_pk_bf16_f32 v109, v109, v112
	global_store_dwordx4 v[110:111], v[106:109], off
	v_pk_mul_f32 v[112:113], v[28:29], v[114:115]
	v_pk_mul_f32 v[114:115], v[26:27], v[118:119]
	v_pk_mul_f32 v[106:107], v[30:31], v[120:121]
	v_pk_mul_f32 v[108:109], v[32:33], v[116:117]
	v_mul_f32_e32 v106, v106, v7
	v_mul_f32_e32 v107, v107, v7
	v_cvt_pk_bf16_f32 v106, v106, v107
	v_mul_f32_e32 v107, v108, v7
	v_mul_f32_e32 v108, v109, v7
	v_cvt_pk_bf16_f32 v107, v107, v108
	v_mul_f32_e32 v108, v114, v7
	v_mul_f32_e32 v109, v115, v7
	v_cvt_pk_bf16_f32 v108, v108, v109
	v_mul_f32_e32 v109, v112, v7
	v_mul_f32_e32 v7, v113, v7
	v_cvt_pk_bf16_f32 v109, v109, v7
	global_store_dwordx4 v[110:111], v[106:109], off offset:64
	v_mov_b64_e32 v[110:111], v[130:131]
	v_mov_b64_e32 v[112:113], v[132:133]
	v_mov_b64_e32 v[106:107], v[126:127]
	v_mov_b64_e32 v[108:109], v[128:129]

.Lew4_5:
	v_mov_b64_e32 v[98:99], v[106:107]
	v_mov_b64_e32 v[102:103], v[110:111]
	s_andn2_b64 vcc, exec, s[52:53]
	v_mov_b64_e32 v[100:101], v[108:109]
	v_mov_b64_e32 v[104:105], v[112:113]
	s_cbranch_vccnz .LBB0_1098
	v_add_u32_e32 v7, 0x80, v200
	v_ashrrev_i32_e32 v98, 31, v7
	v_lshrrev_b32_e32 v98, 19, v98
	v_add_u32_e32 v98, v7, v98
	v_and_b32_e32 v98, 0xffffe000, v98
	v_sub_u32_e32 v98, v7, v98
	v_ashrrev_i32_e32 v99, 31, v98
	v_lshlrev_b64 v[98:99], 7, v[98:99]
	v_lshl_add_u64 v[98:99], v[198:199], 0, v[98:99]
	global_load_dwordx4 v[102:105], v[98:99], off offset:16
	s_nop 0
	global_load_dwordx4 v[98:101], v[98:99], off
	v_mul_f32_e32 v7, v121, v121
	v_mul_f32_e32 v122, v117, v117
	v_fmac_f32_e32 v7, v120, v120
	v_fmac_f32_e32 v122, v116, v116
	v_add_f32_e32 v7, v7, v122
	v_mul_f32_e32 v122, v119, v119
	v_mul_f32_e32 v123, v115, v115
	v_fmac_f32_e32 v122, v118, v118
	v_fmac_f32_e32 v123, v114, v114
	v_add_f32_e32 v122, v122, v123
	v_add_f32_e32 v7, v7, v122
	v_mov_b32_e32 v122, v7
	s_nop 1
	v_permlane16_swap_b32_e32 v7, v122
	v_add_f32_e32 v7, v7, v122
	v_mov_b32_e32 v122, v7
	s_nop 1
	v_permlane32_swap_b32_e32 v7, v122
	v_add_f32_e32 v7, v7, v122
	v_fmamk_f32 v7, v7, 0x3d000000, v217
	v_rsq_f32_e32 v122, v7
	v_mov_b32_e32 v124, v120
	v_mov_b32_e32 v125, v118
	v_mov_b32_e32 v126, v38
	v_pk_mul_f32 v[124:125], v[124:125], v[122:123] op_sel_hi:[1,0]
	v_mov_b32_e32 v127, v34
	v_pk_mul_f32 v[124:125], v[126:127], v[124:125]
	s_nop 0
	v_pk_mul_f32 v[128:129], v[106:107], v[124:125]
	v_pk_mul_f32 v[124:125], v[106:107], v[124:125] op_sel:[1,0] op_sel_hi:[0,1]
	v_add_f32_e32 v123, v124, v125
	v_mov_b32_e32 v124, v121
	v_mov_b32_e32 v125, v119
	v_sub_f32_e32 v7, v128, v129
	v_pk_mul_f32 v[124:125], v[124:125], v[122:123] op_sel_hi:[1,0]
	v_mov_b32_e32 v128, v39
	v_mov_b32_e32 v129, v35
	v_pk_mul_f32 v[124:125], v[128:129], v[124:125]
	v_mul_f32_e32 v134, 0x3e16c740, v123
	v_pk_mul_f32 v[130:131], v[108:109], v[124:125]
	v_pk_mul_f32 v[124:125], v[108:109], v[124:125] op_sel:[1,0] op_sel_hi:[0,1]
	v_sub_f32_e32 v123, v130, v131
	v_mul_f32_e32 v135, 0x3e16c740, v123
	v_add_f32_e32 v123, v124, v125
	v_mov_b32_e32 v124, v116
	v_mov_b32_e32 v125, v114
	v_pk_mul_f32 v[124:125], v[124:125], v[122:123] op_sel_hi:[1,0]
	v_mov_b32_e32 v130, v40
	v_mov_b32_e32 v131, v36
	v_pk_mul_f32 v[124:125], v[130:131], v[124:125]
	v_mul_f32_e32 v136, 0x3e16c740, v123
	v_pk_mul_f32 v[132:133], v[110:111], v[124:125]
	v_pk_mul_f32 v[124:125], v[110:111], v[124:125] op_sel:[1,0] op_sel_hi:[0,1]
	v_sub_f32_e32 v123, v132, v133
	v_mul_f32_e32 v137, 0x3e16c740, v123
	v_add_f32_e32 v123, v124, v125
	v_mov_b32_e32 v124, v117
	v_mov_b32_e32 v125, v115
	v_mul_f32_e32 v138, 0x3e16c740, v123
	v_pk_mul_f32 v[122:123], v[124:125], v[122:123] op_sel_hi:[1,0]
	v_mov_b32_e32 v124, v41
	v_mov_b32_e32 v125, v37
	v_pk_mul_f32 v[122:123], v[124:125], v[122:123]
	v_mul_f32_e32 v7, 0x3e16c740, v7
	v_pk_mul_f32 v[132:133], v[112:113], v[122:123]
	v_pk_mul_f32 v[122:123], v[112:113], v[122:123] op_sel:[1,0] op_sel_hi:[0,1]
	v_add_f32_e32 v122, v122, v123
	v_mul_f32_e32 v139, 0x3e16c740, v122
	v_mov_b64_e32 v[122:123], s[28:29]
	v_sub_f32_e32 v132, v132, v133
	v_mad_i64_i32 v[122:123], s[0:1], v202, s70, v[122:123]
	v_mul_f32_e32 v133, 0x3e16c740, v132
	v_cvt_pk_bf16_f32 v132, v7, v135
	v_lshl_add_u64 v[122:123], v[8:9], 1, v[122:123]
	v_cvt_pk_bf16_f32 v133, v137, v133
	global_store_dwordx2 v[122:123], v[132:133], off offset:128
	v_cvt_pk_bf16_f32 v132, v134, v136
	v_mul_f32_e32 v7, v95, v95
	v_mul_f32_e32 v134, v97, v97
	v_fmac_f32_e32 v7, v94, v94
	v_fmac_f32_e32 v134, v96, v96
	v_add_f32_e32 v7, v7, v134
	v_mul_f32_e32 v134, v91, v91
	v_mul_f32_e32 v135, v93, v93
	v_fmac_f32_e32 v134, v90, v90
	v_fmac_f32_e32 v135, v92, v92
	v_add_f32_e32 v134, v134, v135
	v_add_f32_e32 v7, v7, v134
	v_mov_b32_e32 v134, v7
	s_nop 1
	v_permlane16_swap_b32_e32 v7, v134
	v_add_f32_e32 v7, v7, v134
	v_mov_b32_e32 v134, v7
	s_nop 1
	v_permlane32_swap_b32_e32 v7, v134
	v_add_f32_e32 v7, v7, v134
	v_fmamk_f32 v7, v7, 0x3d000000, v217
	v_rsq_f32_e32 v134, v7
	v_cvt_pk_bf16_f32 v133, v138, v139
	global_store_dwordx2 v[122:123], v[132:133], off offset:160
	v_mov_b32_e32 v132, v94
	v_mov_b32_e32 v133, v90
	v_pk_mul_f32 v[132:133], v[132:133], v[134:135] op_sel_hi:[1,0]
	s_nop 0
	v_pk_mul_f32 v[126:127], v[126:127], v[132:133]
	s_nop 0
	v_pk_mul_f32 v[132:133], v[106:107], v[126:127]
	v_pk_mul_f32 v[126:127], v[106:107], v[126:127] op_sel:[1,0] op_sel_hi:[0,1]
	v_add_f32_e32 v126, v126, v127
	v_sub_f32_e32 v7, v132, v133
	v_mul_f32_e32 v132, 0x3e16c740, v126
	v_mov_b32_e32 v126, v95
	v_mov_b32_e32 v127, v91
	v_pk_mul_f32 v[126:127], v[126:127], v[134:135] op_sel_hi:[1,0]
	v_mul_f32_e32 v7, 0x3e16c740, v7
	v_pk_mul_f32 v[126:127], v[128:129], v[126:127]
	s_nop 0
	v_pk_mul_f32 v[128:129], v[108:109], v[126:127]
	v_pk_mul_f32 v[126:127], v[108:109], v[126:127] op_sel:[1,0] op_sel_hi:[0,1]
	v_add_f32_e32 v126, v126, v127
	v_mul_f32_e32 v135, 0x3e16c740, v126
	v_mov_b32_e32 v126, v96
	v_mov_b32_e32 v127, v92
	v_pk_mul_f32 v[126:127], v[126:127], v[134:135] op_sel_hi:[1,0]
	v_sub_f32_e32 v128, v128, v129
	v_pk_mul_f32 v[126:127], v[130:131], v[126:127]
	v_mul_f32_e32 v133, 0x3e16c740, v128
	v_pk_mul_f32 v[128:129], v[110:111], v[126:127]
	v_pk_mul_f32 v[126:127], v[110:111], v[126:127] op_sel:[1,0] op_sel_hi:[0,1]
	v_add_f32_e32 v126, v126, v127
	v_sub_f32_e32 v128, v128, v129
	v_mul_f32_e32 v129, 0x3e16c740, v126
	v_mov_b32_e32 v126, v97
	v_mov_b32_e32 v127, v93
	v_pk_mul_f32 v[126:127], v[126:127], v[134:135] op_sel_hi:[1,0]
	v_mul_f32_e32 v128, 0x3e16c740, v128
	v_pk_mul_f32 v[124:125], v[124:125], v[126:127]
	s_nop 0
	v_pk_mul_f32 v[126:127], v[112:113], v[124:125]
	v_pk_mul_f32 v[124:125], v[112:113], v[124:125] op_sel:[1,0] op_sel_hi:[0,1]
	v_sub_f32_e32 v126, v126, v127
	v_add_f32_e32 v124, v124, v125
	v_mul_f32_e32 v126, 0x3e16c740, v126
	v_mul_f32_e32 v127, 0x3e16c740, v124
	v_cvt_pk_bf16_f32 v124, v7, v133
	v_cvt_pk_bf16_f32 v125, v128, v126
	global_store_dwordx2 v[122:123], v[124:125], off offset:320
	v_cvt_pk_bf16_f32 v124, v132, v135
	v_cvt_pk_bf16_f32 v125, v129, v127
	global_store_dwordx2 v[122:123], v[124:125], off offset:352

.LBB0_1099:
	s_andn2_b64 vcc, exec, s[52:53]
	s_cbranch_vccnz .LBB0_1101
	v_mul_f32_e32 v7, v121, v121
	s_cmp_eq_u64 s[6:7], 0
	s_cbranch_scc1 .Lew4_6
	s_waitcnt vmcnt(4)
.Lew4_6:
	v_mul_f32_e32 v98, v117, v117
	v_fmac_f32_e32 v7, v120, v120
	v_fmac_f32_e32 v98, v116, v116
	v_add_f32_e32 v7, v7, v98
	v_mul_f32_e32 v98, v119, v119
	v_mul_f32_e32 v99, v115, v115
	v_fmac_f32_e32 v98, v118, v118
	v_fmac_f32_e32 v99, v114, v114
	v_add_f32_e32 v98, v98, v99
	v_add_f32_e32 v7, v7, v98
	v_mul_f32_e32 v98, v95, v95
	v_mul_f32_e32 v99, v97, v97
	v_fmac_f32_e32 v98, v94, v94
	v_fmac_f32_e32 v99, v96, v96
	v_add_f32_e32 v98, v98, v99
	v_mul_f32_e32 v99, v91, v91
	v_mul_f32_e32 v100, v93, v93
	v_fmac_f32_e32 v99, v90, v90
	v_fmac_f32_e32 v100, v92, v92
	v_add_f32_e32 v99, v99, v100
	v_add_f32_e32 v98, v98, v99
	v_add_f32_e32 v7, v7, v98
	v_mov_b32_e32 v98, v7
	s_nop 1
	v_permlane16_swap_b32_e32 v7, v98
	v_add_f32_e32 v7, v7, v98
	v_mov_b32_e32 v98, v7
	s_nop 1
	v_permlane32_swap_b32_e32 v7, v98
	v_add_f32_e32 v7, v7, v98
	v_fmamk_f32 v7, v7, 0x3c800000, v217
	v_rsq_f32_e32 v7, v7
	v_pk_mul_f32 v[98:99], v[38:39], v[120:121]
	v_pk_mul_f32 v[100:101], v[40:41], v[116:117]
	v_pk_mul_f32 v[104:105], v[36:37], v[114:115]
	v_mul_f32_e32 v7, 0x3e16c740, v7
	v_mul_f32_e32 v98, v98, v7
	v_mul_f32_e32 v99, v99, v7
	v_pk_mul_f32 v[114:115], v[34:35], v[118:119]
	v_cvt_pk_bf16_f32 v98, v98, v99
	v_mul_f32_e32 v99, v100, v7
	v_mul_f32_e32 v100, v101, v7
	v_cvt_pk_bf16_f32 v99, v99, v100
	v_mul_f32_e32 v100, v114, v7
	v_mul_f32_e32 v101, v115, v7
	v_mad_i64_i32 v[102:103], s[0:1], v202, s70, v[146:147]
	v_cvt_pk_bf16_f32 v100, v100, v101
	v_mul_f32_e32 v101, v104, v7
	v_pk_mul_f32 v[94:95], v[30:31], v[94:95]
	v_mul_f32_e32 v104, v105, v7
	v_cvt_pk_bf16_f32 v101, v101, v104
	global_store_dwordx4 v[102:103], v[98:101], off
	v_pk_mul_f32 v[96:97], v[32:33], v[96:97]
	s_nop 0
	v_pk_mul_f32 v[98:99], v[28:29], v[92:93]
	v_pk_mul_f32 v[92:93], v[26:27], v[90:91]
	v_mul_f32_e32 v90, v94, v7
	v_mul_f32_e32 v91, v95, v7
	v_cvt_pk_bf16_f32 v90, v90, v91
	v_mul_f32_e32 v91, v96, v7
	v_mul_f32_e32 v92, v92, v7
	v_mul_f32_e32 v93, v93, v7
	v_mul_f32_e32 v94, v97, v7
	v_cvt_pk_bf16_f32 v91, v91, v94
	v_cvt_pk_bf16_f32 v92, v92, v93
	v_mul_f32_e32 v93, v98, v7
	v_mul_f32_e32 v7, v99, v7
	v_cvt_pk_bf16_f32 v93, v93, v7
	global_store_dwordx4 v[102:103], v[90:93], off offset:64
	v_mov_b64_e32 v[102:103], v[110:111]
	v_mov_b64_e32 v[98:99], v[106:107]
	v_mov_b64_e32 v[104:105], v[112:113]
	v_mov_b64_e32 v[100:101], v[108:109]
.LBB0_1101:
	v_add_u32_e32 v116, 0x80, v200
	v_ashrrev_i32_e32 v117, 31, v116
	v_add_u32_e32 v114, 0x90, v200
	s_cmp_eq_u64 s[6:7], 0
	s_cbranch_scc1 .Lew4_7
	s_waitcnt vmcnt(5)
.Lew4_7:
	v_add_u32_e32 v112, 0xa0, v200
	v_add_u32_e32 v110, 0xb0, v200
	v_ashrrev_i32_e32 v115, 31, v114
	v_ashrrev_i32_e32 v113, 31, v112
	v_ashrrev_i32_e32 v111, 31, v110
	v_mov_b32_e32 v118, v236
	v_mov_b32_e32 v119, v237
	v_mov_b32_e32 v120, v238
	v_mov_b32_e32 v121, v239
	v_mov_b32_e32 v106, v240
	v_mov_b32_e32 v107, v241
	v_mov_b32_e32 v108, v242
	v_mov_b32_e32 v109, v243
	v_mov_b32_e32 v94, v244
	v_mov_b32_e32 v95, v245
	v_mov_b32_e32 v96, v246
	v_mov_b32_e32 v97, v247
	v_mov_b32_e32 v90, v248
	v_mov_b32_e32 v91, v249
	v_mov_b32_e32 v92, v250
	v_mov_b32_e32 v93, v251
	s_and_b64 vcc, exec, s[8:9]
	s_mov_b64 s[50:51], -1
	s_cmp_eq_u64 s[6:7], 0
	s_cbranch_scc1 .Lew4_8
	s_waitcnt vmcnt(4)
.Lew4_8:
	v_mov_b32_e32 v122, v119
	v_mov_b32_e32 v123, v120
	v_mov_b32_e32 v119, v121
	v_pk_add_f32 v[118:119], v[122:123], v[118:119]
	s_nop 0
	v_add_f32_e32 v7, v118, v119
	v_fmaak_f32 v7, v3, v7, 0x358637bd
	v_rsq_f32_e32 v126, v7
	s_nop 0
	v_pk_mul_f32 v[122:123], v[88:89], v[126:127] op_sel_hi:[1,0]
	v_pk_mul_f32 v[124:125], v[86:87], v[126:127] op_sel_hi:[1,0]
	v_pk_mul_f32 v[118:119], v[84:85], v[126:127] op_sel_hi:[1,0]
	v_pk_mul_f32 v[120:121], v[82:83], v[126:127] op_sel_hi:[1,0]
	v_pk_mul_f32 v[86:87], v[80:81], v[126:127] op_sel_hi:[1,0]
	v_pk_mul_f32 v[88:89], v[78:79], v[126:127] op_sel_hi:[1,0]
	v_pk_mul_f32 v[82:83], v[76:77], v[126:127] op_sel_hi:[1,0]
	v_pk_mul_f32 v[84:85], v[74:75], v[126:127] op_sel_hi:[1,0]
	s_cbranch_vccnz .LBB0_1111
	s_and_b64 vcc, exec, s[6:7]
	s_cbranch_vccnz .LBB0_1108
	v_lshlrev_b64 v[74:75], 11, v[116:117]
	v_lshl_add_u64 v[74:75], v[4:5], 0, v[74:75]
	s_andn2_b64 vcc, exec, s[26:27]
	s_cbranch_vccnz .LBB0_1105
	v_cvt_pk_bf16_f32 v76, v124, v125
	v_cvt_pk_bf16_f32 v77, v122, v123
	v_cvt_pk_bf16_f32 v78, v120, v121
	v_cvt_pk_bf16_f32 v79, v118, v119
	s_mov_b64 s[50:51], 0
	global_store_dwordx4 v[74:75], v[76:79], off
	s_nop 1
	v_cvt_pk_bf16_f32 v76, v88, v89
	v_cvt_pk_bf16_f32 v77, v86, v87
	v_cvt_pk_bf16_f32 v78, v84, v85
	v_cvt_pk_bf16_f32 v79, v82, v83
	global_store_dwordx4 v[74:75], v[76:79], off offset:64

.LBB0_1111:
	s_andn2_b64 vcc, exec, s[50:51]
	s_cbranch_vccnz .LBB0_1113
	v_mul_f32_e32 v7, v125, v125
	s_cmp_eq_u64 s[6:7], 0
	s_cbranch_scc1 .Lew4_9
	s_waitcnt vmcnt(4)
.Lew4_9:
	v_mul_f32_e32 v74, v123, v123
	v_fmac_f32_e32 v7, v124, v124
	v_fmac_f32_e32 v74, v122, v122
	v_add_f32_e32 v7, v7, v74
	v_mul_f32_e32 v74, v121, v121
	v_mul_f32_e32 v75, v119, v119
	v_fmac_f32_e32 v74, v120, v120
	v_fmac_f32_e32 v75, v118, v118
	v_add_f32_e32 v74, v74, v75
	v_add_f32_e32 v7, v7, v74
	v_mul_f32_e32 v74, v89, v89
	v_mul_f32_e32 v75, v87, v87
	v_fmac_f32_e32 v74, v88, v88
	v_fmac_f32_e32 v75, v86, v86
	v_add_f32_e32 v74, v74, v75
	v_mul_f32_e32 v75, v85, v85
	v_mul_f32_e32 v76, v83, v83
	v_fmac_f32_e32 v75, v84, v84
	v_fmac_f32_e32 v76, v82, v82
	v_add_f32_e32 v75, v75, v76
	v_add_f32_e32 v74, v74, v75
	v_add_f32_e32 v7, v7, v74
	v_mov_b32_e32 v74, v7
	s_nop 1
	v_permlane16_swap_b32_e32 v7, v74
	v_add_f32_e32 v7, v7, v74
	v_mov_b32_e32 v74, v7
	s_nop 1
	v_permlane32_swap_b32_e32 v7, v74
	v_add_f32_e32 v7, v7, v74
	v_fmamk_f32 v7, v7, 0x3c800000, v217
	v_rsq_f32_e32 v7, v7
	v_pk_mul_f32 v[74:75], v[38:39], v[124:125]
	v_pk_mul_f32 v[76:77], v[40:41], v[122:123]
	v_mad_i64_i32 v[78:79], s[0:1], v116, s70, v[146:147]
	v_mul_f32_e32 v7, 0x3e16c740, v7
	v_mul_f32_e32 v74, v74, v7
	v_mul_f32_e32 v75, v75, v7
	v_pk_mul_f32 v[116:117], v[34:35], v[120:121]
	v_cvt_pk_bf16_f32 v74, v74, v75
	v_mul_f32_e32 v75, v76, v7
	v_mul_f32_e32 v76, v77, v7
	v_pk_mul_f32 v[80:81], v[36:37], v[118:119]
	v_cvt_pk_bf16_f32 v75, v75, v76
	v_mul_f32_e32 v76, v116, v7
	v_mul_f32_e32 v77, v117, v7
	v_cvt_pk_bf16_f32 v76, v76, v77
	v_mul_f32_e32 v77, v80, v7
	v_mul_f32_e32 v80, v81, v7
	v_cvt_pk_bf16_f32 v77, v77, v80
	global_store_dwordx4 v[78:79], v[74:77], off
	v_pk_mul_f32 v[80:81], v[28:29], v[82:83]
	v_pk_mul_f32 v[82:83], v[26:27], v[84:85]
	v_pk_mul_f32 v[74:75], v[30:31], v[88:89]
	v_pk_mul_f32 v[76:77], v[32:33], v[86:87]
	v_mul_f32_e32 v74, v74, v7
	v_mul_f32_e32 v75, v75, v7
	v_cvt_pk_bf16_f32 v74, v74, v75
	v_mul_f32_e32 v75, v76, v7
	v_mul_f32_e32 v76, v77, v7
	v_cvt_pk_bf16_f32 v75, v75, v76
	v_mul_f32_e32 v76, v82, v7
	v_mul_f32_e32 v77, v83, v7
	v_cvt_pk_bf16_f32 v76, v76, v77
	v_mul_f32_e32 v77, v80, v7
	v_mul_f32_e32 v7, v81, v7
	v_cvt_pk_bf16_f32 v77, v77, v7
	global_store_dwordx4 v[78:79], v[74:77], off offset:64
	v_mov_b64_e32 v[78:79], v[102:103]
	v_mov_b64_e32 v[80:81], v[104:105]
	v_mov_b64_e32 v[74:75], v[98:99]
	v_mov_b64_e32 v[76:77], v[100:101]

.Lew4_10:
	v_add_f32_e32 v7, v106, v107
	v_add_f32_e32 v82, v108, v109
	v_add_f32_e32 v7, v7, v82
	v_fmaak_f32 v7, v3, v7, 0x358637bd
	v_rsq_f32_e32 v98, v7
	s_and_b64 vcc, exec, s[8:9]
	s_mov_b64 s[50:51], -1
	v_pk_mul_f32 v[84:85], v[72:73], v[98:99] op_sel_hi:[1,0]
	v_pk_mul_f32 v[88:89], v[70:71], v[98:99] op_sel_hi:[1,0]
	v_pk_mul_f32 v[82:83], v[68:69], v[98:99] op_sel_hi:[1,0]
	v_pk_mul_f32 v[86:87], v[66:67], v[98:99] op_sel_hi:[1,0]
	v_pk_mul_f32 v[68:69], v[64:65], v[98:99] op_sel_hi:[1,0]
	v_pk_mul_f32 v[72:73], v[62:63], v[98:99] op_sel_hi:[1,0]
	v_pk_mul_f32 v[66:67], v[60:61], v[98:99] op_sel_hi:[1,0]
	v_pk_mul_f32 v[70:71], v[58:59], v[98:99] op_sel_hi:[1,0]
	s_cbranch_vccnz .LBB0_1123
	s_and_b64 vcc, exec, s[6:7]
	s_cbranch_vccnz .LBB0_1120
	v_lshlrev_b64 v[58:59], 11, v[114:115]
	v_lshl_add_u64 v[58:59], v[4:5], 0, v[58:59]
	s_andn2_b64 vcc, exec, s[26:27]
	s_cbranch_vccnz .LBB0_1117
	v_cvt_pk_bf16_f32 v60, v88, v89
	v_cvt_pk_bf16_f32 v61, v84, v85
	v_cvt_pk_bf16_f32 v62, v86, v87
	v_cvt_pk_bf16_f32 v63, v82, v83
	s_mov_b64 s[50:51], 0
	global_store_dwordx4 v[58:59], v[60:63], off
	s_nop 1
	v_cvt_pk_bf16_f32 v60, v72, v73
	v_cvt_pk_bf16_f32 v61, v68, v69
	v_cvt_pk_bf16_f32 v62, v70, v71
	v_cvt_pk_bf16_f32 v63, v66, v67
	global_store_dwordx4 v[58:59], v[60:63], off offset:64

.LBB0_1123:
	s_andn2_b64 vcc, exec, s[50:51]
	s_cbranch_vccnz .LBB0_1125
	v_mul_f32_e32 v7, v89, v89
	s_cmp_eq_u64 s[6:7], 0
	s_cbranch_scc1 .Lew4_11
	s_waitcnt vmcnt(4)
.Lew4_11:
	v_mul_f32_e32 v58, v85, v85
	v_fmac_f32_e32 v7, v88, v88
	v_fmac_f32_e32 v58, v84, v84
	v_add_f32_e32 v7, v7, v58
	v_mul_f32_e32 v58, v87, v87
	v_mul_f32_e32 v59, v83, v83
	v_fmac_f32_e32 v58, v86, v86
	v_fmac_f32_e32 v59, v82, v82
	v_add_f32_e32 v58, v58, v59
	v_add_f32_e32 v7, v7, v58
	v_mul_f32_e32 v58, v73, v73
	v_mul_f32_e32 v59, v69, v69
	v_fmac_f32_e32 v58, v72, v72
	v_fmac_f32_e32 v59, v68, v68
	v_add_f32_e32 v58, v58, v59
	v_mul_f32_e32 v59, v71, v71
	v_mul_f32_e32 v60, v67, v67
	v_fmac_f32_e32 v59, v70, v70
	v_fmac_f32_e32 v60, v66, v66
	v_add_f32_e32 v59, v59, v60
	v_add_f32_e32 v58, v58, v59
	v_add_f32_e32 v7, v7, v58
	v_mov_b32_e32 v58, v7
	s_nop 1
	v_permlane16_swap_b32_e32 v7, v58
	v_add_f32_e32 v7, v7, v58
	v_mov_b32_e32 v58, v7
	s_nop 1
	v_permlane32_swap_b32_e32 v7, v58
	v_add_f32_e32 v7, v7, v58
	v_fmamk_f32 v7, v7, 0x3c800000, v217
	v_rsq_f32_e32 v7, v7
	v_pk_mul_f32 v[58:59], v[38:39], v[88:89]
	v_pk_mul_f32 v[60:61], v[40:41], v[84:85]
	v_pk_mul_f32 v[64:65], v[36:37], v[82:83]
	v_mul_f32_e32 v7, 0x3e16c740, v7
	v_mul_f32_e32 v58, v58, v7
	v_mul_f32_e32 v59, v59, v7
	v_pk_mul_f32 v[82:83], v[34:35], v[86:87]
	v_cvt_pk_bf16_f32 v58, v58, v59
	v_mul_f32_e32 v59, v60, v7
	v_mul_f32_e32 v60, v61, v7
	v_cvt_pk_bf16_f32 v59, v59, v60
	v_mul_f32_e32 v60, v82, v7
	v_mul_f32_e32 v61, v83, v7
	v_mad_i64_i32 v[62:63], s[0:1], v114, s70, v[146:147]
	v_cvt_pk_bf16_f32 v60, v60, v61
	v_mul_f32_e32 v61, v64, v7
	v_mul_f32_e32 v64, v65, v7
	v_cvt_pk_bf16_f32 v61, v61, v64
	global_store_dwordx4 v[62:63], v[58:61], off
	v_pk_mul_f32 v[64:65], v[28:29], v[66:67]
	v_pk_mul_f32 v[66:67], v[26:27], v[70:71]
	v_pk_mul_f32 v[58:59], v[30:31], v[72:73]
	v_pk_mul_f32 v[60:61], v[32:33], v[68:69]
	v_mul_f32_e32 v58, v58, v7
	v_mul_f32_e32 v59, v59, v7
	v_cvt_pk_bf16_f32 v58, v58, v59
	v_mul_f32_e32 v59, v60, v7
	v_mul_f32_e32 v60, v61, v7
	v_cvt_pk_bf16_f32 v59, v59, v60
	v_mul_f32_e32 v60, v66, v7
	v_mul_f32_e32 v61, v67, v7
	v_cvt_pk_bf16_f32 v60, v60, v61
	v_mul_f32_e32 v61, v64, v7
	v_mul_f32_e32 v7, v65, v7
	v_cvt_pk_bf16_f32 v61, v61, v7
	global_store_dwordx4 v[62:63], v[58:61], off offset:64
	v_mov_b64_e32 v[62:63], v[78:79]
	v_mov_b64_e32 v[64:65], v[80:81]
	v_mov_b64_e32 v[58:59], v[74:75]
	v_mov_b64_e32 v[60:61], v[76:77]

.Lew4_12:
	v_add_f32_e32 v7, v94, v95
	v_add_f32_e32 v66, v96, v97
	v_add_f32_e32 v7, v7, v66
	v_fmaak_f32 v7, v3, v7, 0x358637bd
	v_rsq_f32_e32 v74, v7
	s_and_b64 vcc, exec, s[8:9]
	s_mov_b64 s[50:51], -1
	v_pk_mul_f32 v[68:69], v[56:57], v[74:75] op_sel_hi:[1,0]
	v_pk_mul_f32 v[72:73], v[54:55], v[74:75] op_sel_hi:[1,0]
	v_pk_mul_f32 v[66:67], v[52:53], v[74:75] op_sel_hi:[1,0]
	v_pk_mul_f32 v[70:71], v[50:51], v[74:75] op_sel_hi:[1,0]
	v_pk_mul_f32 v[52:53], v[48:49], v[74:75] op_sel_hi:[1,0]
	v_pk_mul_f32 v[56:57], v[46:47], v[74:75] op_sel_hi:[1,0]
	v_pk_mul_f32 v[50:51], v[44:45], v[74:75] op_sel_hi:[1,0]
	v_pk_mul_f32 v[54:55], v[42:43], v[74:75] op_sel_hi:[1,0]
	s_cbranch_vccnz .LBB0_1135
	s_and_b64 vcc, exec, s[6:7]
	s_cbranch_vccnz .LBB0_1132
	v_lshlrev_b64 v[42:43], 11, v[112:113]
	v_lshl_add_u64 v[42:43], v[4:5], 0, v[42:43]
	s_andn2_b64 vcc, exec, s[26:27]
	s_cbranch_vccnz .LBB0_1129
	v_cvt_pk_bf16_f32 v44, v72, v73
	v_cvt_pk_bf16_f32 v45, v68, v69
	v_cvt_pk_bf16_f32 v46, v70, v71
	v_cvt_pk_bf16_f32 v47, v66, v67
	s_mov_b64 s[50:51], 0
	global_store_dwordx4 v[42:43], v[44:47], off
	s_nop 1
	v_cvt_pk_bf16_f32 v44, v56, v57
	v_cvt_pk_bf16_f32 v45, v52, v53
	v_cvt_pk_bf16_f32 v46, v54, v55
	v_cvt_pk_bf16_f32 v47, v50, v51
	global_store_dwordx4 v[42:43], v[44:47], off offset:64

.LBB0_1135:
	s_andn2_b64 vcc, exec, s[50:51]
	s_cbranch_vccnz .LBB0_1137
	v_mul_f32_e32 v7, v73, v73
	s_cmp_eq_u64 s[6:7], 0
	s_cbranch_scc1 .Lew4_13
	s_waitcnt vmcnt(5)
.Lew4_13:
	v_mul_f32_e32 v42, v69, v69
	v_fmac_f32_e32 v7, v72, v72
	v_fmac_f32_e32 v42, v68, v68
	v_add_f32_e32 v7, v7, v42
	v_mul_f32_e32 v42, v71, v71
	v_mul_f32_e32 v43, v67, v67
	v_fmac_f32_e32 v42, v70, v70
	v_fmac_f32_e32 v43, v66, v66
	v_add_f32_e32 v42, v42, v43
	v_add_f32_e32 v7, v7, v42
	v_mul_f32_e32 v42, v57, v57
	v_mul_f32_e32 v43, v53, v53
	v_fmac_f32_e32 v42, v56, v56
	v_fmac_f32_e32 v43, v52, v52
	v_add_f32_e32 v42, v42, v43
	v_mul_f32_e32 v43, v55, v55
	v_mul_f32_e32 v44, v51, v51
	v_fmac_f32_e32 v43, v54, v54
	v_fmac_f32_e32 v44, v50, v50
	v_add_f32_e32 v43, v43, v44
	v_add_f32_e32 v42, v42, v43
	v_add_f32_e32 v7, v7, v42
	v_mov_b32_e32 v42, v7
	s_nop 1
	v_permlane16_swap_b32_e32 v7, v42
	v_add_f32_e32 v7, v7, v42
	v_mov_b32_e32 v42, v7
	s_nop 1
	v_permlane32_swap_b32_e32 v7, v42
	v_add_f32_e32 v7, v7, v42
	v_fmamk_f32 v7, v7, 0x3c800000, v217
	v_rsq_f32_e32 v7, v7
	v_pk_mul_f32 v[42:43], v[38:39], v[72:73]
	v_pk_mul_f32 v[44:45], v[40:41], v[68:69]
	s_cmp_eq_u64 s[6:7], 0
	s_cbranch_scc1 .Lew4_14
	s_waitcnt vmcnt(4)
.Lew4_14:
	v_pk_mul_f32 v[48:49], v[36:37], v[66:67]
	v_mul_f32_e32 v7, 0x3e16c740, v7
	v_mul_f32_e32 v42, v42, v7
	v_mul_f32_e32 v43, v43, v7
	v_pk_mul_f32 v[66:67], v[34:35], v[70:71]
	v_cvt_pk_bf16_f32 v42, v42, v43
	v_mul_f32_e32 v43, v44, v7
	v_mul_f32_e32 v44, v45, v7
	v_cvt_pk_bf16_f32 v43, v43, v44
	v_mul_f32_e32 v44, v66, v7
	v_mul_f32_e32 v45, v67, v7
	v_mad_i64_i32 v[46:47], s[0:1], v112, s70, v[146:147]
	v_cvt_pk_bf16_f32 v44, v44, v45
	v_mul_f32_e32 v45, v48, v7
	v_mul_f32_e32 v48, v49, v7
	v_cvt_pk_bf16_f32 v45, v45, v48
	global_store_dwordx4 v[46:47], v[42:45], off
	v_pk_mul_f32 v[48:49], v[28:29], v[50:51]
	v_pk_mul_f32 v[50:51], v[26:27], v[54:55]
	v_pk_mul_f32 v[42:43], v[30:31], v[56:57]
	v_pk_mul_f32 v[44:45], v[32:33], v[52:53]
	v_mul_f32_e32 v42, v42, v7
	v_mul_f32_e32 v43, v43, v7
	v_cvt_pk_bf16_f32 v42, v42, v43
	v_mul_f32_e32 v43, v44, v7
	v_mul_f32_e32 v44, v45, v7
	v_cvt_pk_bf16_f32 v43, v43, v44
	v_mul_f32_e32 v44, v50, v7
	v_mul_f32_e32 v45, v51, v7
	v_cvt_pk_bf16_f32 v44, v44, v45
	v_mul_f32_e32 v45, v48, v7
	v_mul_f32_e32 v7, v49, v7
	v_cvt_pk_bf16_f32 v45, v45, v7
	global_store_dwordx4 v[46:47], v[42:45], off offset:64
	v_mov_b64_e32 v[46:47], v[58:59]
	v_mov_b64_e32 v[48:49], v[60:61]
	v_mov_b64_e32 v[42:43], v[62:63]
	v_mov_b64_e32 v[44:45], v[64:65]

.Lew4_15:
	v_add_f32_e32 v7, v90, v91
	v_add_f32_e32 v50, v92, v93
	v_add_f32_e32 v7, v7, v50
	v_fmaak_f32 v3, v3, v7, 0x358637bd
	v_rsq_f32_e32 v50, v3
	s_and_b64 vcc, exec, s[8:9]
	s_mov_b64 s[8:9], -1
	v_pk_mul_f32 v[24:25], v[24:25], v[50:51] op_sel_hi:[1,0]
	v_pk_mul_f32 v[22:23], v[22:23], v[50:51] op_sel_hi:[1,0]
	v_pk_mul_f32 v[20:21], v[20:21], v[50:51] op_sel_hi:[1,0]
	v_pk_mul_f32 v[18:19], v[18:19], v[50:51] op_sel_hi:[1,0]
	v_pk_mul_f32 v[16:17], v[16:17], v[50:51] op_sel_hi:[1,0]
	v_pk_mul_f32 v[14:15], v[14:15], v[50:51] op_sel_hi:[1,0]
	v_pk_mul_f32 v[12:13], v[12:13], v[50:51] op_sel_hi:[1,0]
	v_pk_mul_f32 v[10:11], v[10:11], v[50:51] op_sel_hi:[1,0]
	s_cbranch_vccz .LBB0_1140
	s_andn2_b64 vcc, exec, s[8:9]
	s_cbranch_vccz .LBB0_1149
